# W_in epilogue: bf16 packing reads the accumulators directly (the 8 staging moves per store removed, gate path packs its own values)
# speedup vs baseline: 1.0051x; 1.0051x over previous
; __device__ __forceinline__ unsigned cvt_pk_bf16(float lo, float hi) { unsigned r; asm volatile("v_cvt_pk_bf16_f32 %0, %1, %2" : "=v"(r) : "v"(lo), "v"(hi)); return r; }
;     __device__ __forceinline__ void operator()(const f32x4 (&acc)[2][2][4][2], const Unit& u, int wr, int wc, int fr, int fq) const {
;         const int row0 = u.pm * BM + wr * 64 + fr; const bool isg = u.pn >= 30;
;         bf16_t* base = isg ? Gt : Z; const int ld = isg ? 3072 : 7680; const int col0 = (isg ? (u.pn - 30) : u.pn) * BM + wc * 32 + 8 * fq;
; #pragma unroll
;         for (int ai = 0; ai < 2; ++ai)
; #pragma unroll
;             for (int m = 0; m < 4; ++m)
; #pragma unroll
;                 for (int bj = 0; bj < 2; ++bj) {
;                     f32x4 v0 = acc[ai][bj][m][0], v1 = acc[ai][bj][m][1];
;                     if (isg) {
; #pragma unroll
;                         for (int j = 0; j < 4; ++j) { v0[j] = 1.f + __builtin_amdgcn_exp2f(v0[j] * -1.44269504088896341f); v1[j] = 1.f + __builtin_amdgcn_exp2f(v1[j] * -1.44269504088896341f); }
;                     }
;                     u32x4 w; w.x = cvt_pk_bf16(v0[0], v0[1]); w.y = cvt_pk_bf16(v0[2], v0[3]); w.z = cvt_pk_bf16(v1[0], v1[1]); w.w = cvt_pk_bf16(v1[2], v1[3]);
;                     *(u32x4*)(base + (size_t)(row0 + ai * HALF + m * 16) * ld + col0 + bj * HALF) = w;
;                 }
;     }
.LBB0_324:
	s_lshl_b32 s14, s54, 8
	s_lshl_b32 s57, s55, 6
	s_add_i32 s57, s57, s14
	s_and_b64 s[58:59], s[46:47], exec
	s_movk_i32 s14, 0xc00
	s_cselect_b32 s15, s43, s15
	s_cselect_b32 s14, s14, 0x1e00
	s_cselect_b32 s42, s56, s42
	v_mov_b32_e32 v131, s15
	s_lshl_b32 s15, s53, 8
	s_add_i32 s56, s15, 0xffffe200
	v_mov_b32_e32 v130, s42
	s_and_b64 s[42:43], s[46:47], exec
	s_cselect_b32 s15, s56, s15
	s_lshl_b32 s42, s34, 5
	s_add_i32 s42, s42, s15
	v_lshl_add_u32 v146, v159, 3, s42
	v_add_u32_e32 v161, s57, v160
	v_ashrrev_i32_e32 v147, 31, v146
	v_lshl_add_u64 v[130:131], v[146:147], 1, v[130:131]
	v_mad_i64_i32 v[146:147], s[42:43], s14, v161, 0
	v_lshl_add_u64 v[146:147], v[146:147], 1, v[130:131]
	v_cvt_pk_bf16_f32 v152, v152, v153
	v_cvt_pk_bf16_f32 v153, v150, v151
	v_cvt_pk_bf16_f32 v154, v154, v155
	v_cvt_pk_bf16_f32 v155, v148, v149
	v_cndmask_b32_e64 v148, 0, 1, s[46:47]
	ds_bpermute_b32 v152, v248, v152
	ds_bpermute_b32 v153, v248, v153
	ds_bpermute_b32 v154, v248, v154
	ds_bpermute_b32 v155, v248, v155
	s_waitcnt lgkmcnt(0)
	global_store_dwordx4 v[146:147], v[152:155], off
	v_cmp_ne_u32_e64 s[42:43], 1, v148
	s_andn2_b64 vcc, exec, s[46:47]
	s_cbranch_vccnz .LBB0_326
	v_mul_f32_e32 v149, 0xbfb8aa3b, v114
	v_mul_f32_e32 v151, 0xbfb8aa3b, v116
	v_mul_f32_e32 v148, 0xbfb8aa3b, v122
	v_exp_f32_e32 v154, v149
	v_mul_f32_e32 v149, 0xbfb8aa3b, v123
	v_mul_f32_e32 v152, 0xbfb8aa3b, v115
	v_mul_f32_e32 v150, 0xbfb8aa3b, v124
	v_exp_f32_e32 v162, v151
	v_mul_f32_e32 v151, 0xbfb8aa3b, v125
	v_mul_f32_e32 v153, 0xbfb8aa3b, v117
	v_exp_f32_e32 v148, v148
	v_exp_f32_e32 v149, v149
	v_exp_f32_e32 v150, v150
	v_exp_f32_e32 v151, v151
	v_exp_f32_e32 v163, v153
	v_exp_f32_e32 v155, v152
	v_pk_add_f32 v[152:153], v[148:149], 1.0 op_sel_hi:[1,0]
	v_pk_add_f32 v[150:151], v[150:151], 1.0 op_sel_hi:[1,0]
	v_pk_add_f32 v[148:149], v[162:163], 1.0 op_sel_hi:[1,0]
	v_pk_add_f32 v[154:155], v[154:155], 1.0 op_sel_hi:[1,0]
	v_cvt_pk_bf16_f32 v152, v152, v153
	v_cvt_pk_bf16_f32 v153, v150, v151
	s_nop 0
	v_cvt_pk_bf16_f32 v154, v154, v155
	v_cvt_pk_bf16_f32 v155, v148, v149
	s_branch .Lwin_join_0
.LBB0_326:
	v_cvt_pk_bf16_f32 v152, v122, v123
	v_cvt_pk_bf16_f32 v153, v124, v125
	s_nop 0
	v_cvt_pk_bf16_f32 v154, v114, v115
	v_cvt_pk_bf16_f32 v155, v116, v117
.Lwin_join_0:
	ds_bpermute_b32 v152, v248, v152
	ds_bpermute_b32 v153, v248, v153
	ds_bpermute_b32 v154, v248, v154
	ds_bpermute_b32 v155, v248, v155
	s_waitcnt lgkmcnt(0)
	global_store_dwordx4 v[146:147], v[152:155], off offset:256
	s_and_b64 vcc, exec, s[42:43]
	s_cbranch_vccnz .LBB0_328
	v_mul_f32_e32 v147, 0xbfb8aa3b, v102
	v_mul_f32_e32 v149, 0xbfb8aa3b, v104
	v_mul_f32_e32 v146, 0xbfb8aa3b, v110
	v_exp_f32_e32 v154, v147
	v_mul_f32_e32 v147, 0xbfb8aa3b, v111
	v_mul_f32_e32 v150, 0xbfb8aa3b, v103
	v_mul_f32_e32 v148, 0xbfb8aa3b, v112
	v_exp_f32_e32 v162, v149
	v_mul_f32_e32 v149, 0xbfb8aa3b, v113
	v_mul_f32_e32 v151, 0xbfb8aa3b, v105
	v_exp_f32_e32 v146, v146
	v_exp_f32_e32 v147, v147
	v_exp_f32_e32 v148, v148
	v_exp_f32_e32 v149, v149
	v_exp_f32_e32 v163, v151
	v_exp_f32_e32 v155, v150
	v_pk_add_f32 v[152:153], v[146:147], 1.0 op_sel_hi:[1,0]
	v_pk_add_f32 v[150:151], v[148:149], 1.0 op_sel_hi:[1,0]
	v_pk_add_f32 v[148:149], v[162:163], 1.0 op_sel_hi:[1,0]
	v_pk_add_f32 v[154:155], v[154:155], 1.0 op_sel_hi:[1,0]
	v_add_u32_e32 v146, 16, v161
	v_mad_i64_i32 v[146:147], s[46:47], s14, v146, 0
	v_lshl_add_u64 v[146:147], v[146:147], 1, v[130:131]
	v_cvt_pk_bf16_f32 v152, v152, v153
	v_cvt_pk_bf16_f32 v153, v150, v151
	v_cvt_pk_bf16_f32 v154, v154, v155
	v_cvt_pk_bf16_f32 v155, v148, v149
	s_branch .Lwin_join_1
.LBB0_328:
	v_add_u32_e32 v146, 16, v161
	v_mad_i64_i32 v[146:147], s[46:47], s14, v146, 0
	v_lshl_add_u64 v[146:147], v[146:147], 1, v[130:131]
	v_cvt_pk_bf16_f32 v152, v110, v111
	v_cvt_pk_bf16_f32 v153, v112, v113
	v_cvt_pk_bf16_f32 v154, v102, v103
	v_cvt_pk_bf16_f32 v155, v104, v105
.Lwin_join_1:
	ds_bpermute_b32 v152, v248, v152
	ds_bpermute_b32 v153, v248, v153
	ds_bpermute_b32 v154, v248, v154
	ds_bpermute_b32 v155, v248, v155
	s_waitcnt lgkmcnt(0)
	global_store_dwordx4 v[146:147], v[152:155], off
	s_and_b64 vcc, exec, s[42:43]
	s_cbranch_vccnz .LBB0_330
	v_mul_f32_e32 v149, 0xbfb8aa3b, v98
	v_mul_f32_e32 v151, 0xbfb8aa3b, v100
	v_mul_f32_e32 v148, 0xbfb8aa3b, v106
	v_exp_f32_e32 v154, v149
	v_mul_f32_e32 v149, 0xbfb8aa3b, v107
	v_mul_f32_e32 v152, 0xbfb8aa3b, v99
	v_mul_f32_e32 v150, 0xbfb8aa3b, v108
	v_exp_f32_e32 v162, v151
	v_mul_f32_e32 v151, 0xbfb8aa3b, v109
	v_mul_f32_e32 v153, 0xbfb8aa3b, v101
	v_exp_f32_e32 v148, v148
	v_exp_f32_e32 v149, v149
	v_exp_f32_e32 v150, v150
	v_exp_f32_e32 v151, v151
	v_exp_f32_e32 v163, v153
	v_exp_f32_e32 v155, v152
	v_pk_add_f32 v[152:153], v[148:149], 1.0 op_sel_hi:[1,0]
	v_pk_add_f32 v[150:151], v[150:151], 1.0 op_sel_hi:[1,0]
	v_pk_add_f32 v[148:149], v[162:163], 1.0 op_sel_hi:[1,0]
	v_pk_add_f32 v[154:155], v[154:155], 1.0 op_sel_hi:[1,0]
	v_cvt_pk_bf16_f32 v152, v152, v153
	v_cvt_pk_bf16_f32 v153, v150, v151
	s_nop 0
	v_cvt_pk_bf16_f32 v154, v154, v155
	v_cvt_pk_bf16_f32 v155, v148, v149
	s_branch .Lwin_join_2
.LBB0_330:
	v_cvt_pk_bf16_f32 v152, v106, v107
	v_cvt_pk_bf16_f32 v153, v108, v109
	s_nop 0
	v_cvt_pk_bf16_f32 v154, v98, v99
	v_cvt_pk_bf16_f32 v155, v100, v101
; __device__ __forceinline__ unsigned cvt_pk_bf16(float lo, float hi) { unsigned r; asm volatile("v_cvt_pk_bf16_f32 %0, %1, %2" : "=v"(r) : "v"(lo), "v"(hi)); return r; }
;     __device__ __forceinline__ void operator()(const f32x4 (&acc)[2][2][4][2], const Unit& u, int wr, int wc, int fr, int fq) const {
;         const int row0 = u.pm * BM + wr * 64 + fr; const bool isg = u.pn >= 30;
;         bf16_t* base = isg ? Gt : Z; const int ld = isg ? 3072 : 7680; const int col0 = (isg ? (u.pn - 30) : u.pn) * BM + wc * 32 + 8 * fq;
; #pragma unroll
;         for (int ai = 0; ai < 2; ++ai)
; #pragma unroll
;             for (int m = 0; m < 4; ++m)
; #pragma unroll
;                 for (int bj = 0; bj < 2; ++bj) {
;                     f32x4 v0 = acc[ai][bj][m][0], v1 = acc[ai][bj][m][1];
;                     if (isg) {
; #pragma unroll
;                         for (int j = 0; j < 4; ++j) { v0[j] = 1.f + __builtin_amdgcn_exp2f(v0[j] * -1.44269504088896341f); v1[j] = 1.f + __builtin_amdgcn_exp2f(v1[j] * -1.44269504088896341f); }
;                     }
;                     u32x4 w; w.x = cvt_pk_bf16(v0[0], v0[1]); w.y = cvt_pk_bf16(v0[2], v0[3]); w.z = cvt_pk_bf16(v1[0], v1[1]); w.w = cvt_pk_bf16(v1[2], v1[3]);
;                     *(u32x4*)(base + (size_t)(row0 + ai * HALF + m * 16) * ld + col0 + bj * HALF) = w;
;                 }
;     }
.Lwin_join_2:
	ds_bpermute_b32 v152, v248, v152
	ds_bpermute_b32 v153, v248, v153
	ds_bpermute_b32 v154, v248, v154
	ds_bpermute_b32 v155, v248, v155
	s_waitcnt lgkmcnt(0)
	global_store_dwordx4 v[146:147], v[152:155], off offset:256
	s_and_b64 vcc, exec, s[42:43]
	s_cbranch_vccnz .LBB0_332
	v_mul_f32_e32 v147, 0xbfb8aa3b, v86
	v_mul_f32_e32 v149, 0xbfb8aa3b, v88
	v_mul_f32_e32 v146, 0xbfb8aa3b, v94
	v_exp_f32_e32 v154, v147
	v_mul_f32_e32 v147, 0xbfb8aa3b, v95
	v_mul_f32_e32 v150, 0xbfb8aa3b, v87
	v_mul_f32_e32 v148, 0xbfb8aa3b, v96
	v_exp_f32_e32 v162, v149
	v_mul_f32_e32 v149, 0xbfb8aa3b, v97
	v_mul_f32_e32 v151, 0xbfb8aa3b, v89
	v_exp_f32_e32 v146, v146
	v_exp_f32_e32 v147, v147
	v_exp_f32_e32 v148, v148
	v_exp_f32_e32 v149, v149
	v_exp_f32_e32 v163, v151
	v_exp_f32_e32 v155, v150
	v_pk_add_f32 v[152:153], v[146:147], 1.0 op_sel_hi:[1,0]
	v_pk_add_f32 v[150:151], v[148:149], 1.0 op_sel_hi:[1,0]
	v_pk_add_f32 v[148:149], v[162:163], 1.0 op_sel_hi:[1,0]
	v_pk_add_f32 v[154:155], v[154:155], 1.0 op_sel_hi:[1,0]
	v_add_u32_e32 v146, 32, v161
	v_mad_i64_i32 v[146:147], s[46:47], s14, v146, 0
	v_lshl_add_u64 v[146:147], v[146:147], 1, v[130:131]
	v_cvt_pk_bf16_f32 v152, v152, v153
	v_cvt_pk_bf16_f32 v153, v150, v151
	v_cvt_pk_bf16_f32 v154, v154, v155
	v_cvt_pk_bf16_f32 v155, v148, v149
	s_branch .Lwin_join_3
.LBB0_332:
	v_add_u32_e32 v146, 32, v161
	v_mad_i64_i32 v[146:147], s[46:47], s14, v146, 0
	v_lshl_add_u64 v[146:147], v[146:147], 1, v[130:131]
	v_cvt_pk_bf16_f32 v152, v94, v95
	v_cvt_pk_bf16_f32 v153, v96, v97
	v_cvt_pk_bf16_f32 v154, v86, v87
	v_cvt_pk_bf16_f32 v155, v88, v89
.Lwin_join_3:
	ds_bpermute_b32 v152, v248, v152
	ds_bpermute_b32 v153, v248, v153
	ds_bpermute_b32 v154, v248, v154
	ds_bpermute_b32 v155, v248, v155
	s_waitcnt lgkmcnt(0)
	global_store_dwordx4 v[146:147], v[152:155], off
	s_and_b64 vcc, exec, s[42:43]
	s_cbranch_vccnz .LBB0_334
	v_mul_f32_e32 v149, 0xbfb8aa3b, v82
	v_mul_f32_e32 v151, 0xbfb8aa3b, v84
	v_mul_f32_e32 v148, 0xbfb8aa3b, v90
	v_exp_f32_e32 v154, v149
	v_mul_f32_e32 v149, 0xbfb8aa3b, v91
	v_mul_f32_e32 v152, 0xbfb8aa3b, v83
	v_mul_f32_e32 v150, 0xbfb8aa3b, v92
	v_exp_f32_e32 v162, v151
	v_mul_f32_e32 v151, 0xbfb8aa3b, v93
	v_mul_f32_e32 v153, 0xbfb8aa3b, v85
	v_exp_f32_e32 v148, v148
	v_exp_f32_e32 v149, v149
	v_exp_f32_e32 v150, v150
	v_exp_f32_e32 v151, v151
	v_exp_f32_e32 v163, v153
	v_exp_f32_e32 v155, v152
	v_pk_add_f32 v[152:153], v[148:149], 1.0 op_sel_hi:[1,0]
	v_pk_add_f32 v[150:151], v[150:151], 1.0 op_sel_hi:[1,0]
	v_pk_add_f32 v[148:149], v[162:163], 1.0 op_sel_hi:[1,0]
	v_pk_add_f32 v[154:155], v[154:155], 1.0 op_sel_hi:[1,0]
	v_cvt_pk_bf16_f32 v152, v152, v153
	v_cvt_pk_bf16_f32 v153, v150, v151
	s_nop 0
	v_cvt_pk_bf16_f32 v154, v154, v155
	v_cvt_pk_bf16_f32 v155, v148, v149
	s_branch .Lwin_join_4
.LBB0_334:
	v_cvt_pk_bf16_f32 v152, v90, v91
	v_cvt_pk_bf16_f32 v153, v92, v93
	s_nop 0
	v_cvt_pk_bf16_f32 v154, v82, v83
	v_cvt_pk_bf16_f32 v155, v84, v85
.Lwin_join_4:
	ds_bpermute_b32 v152, v248, v152
	ds_bpermute_b32 v153, v248, v153
	ds_bpermute_b32 v154, v248, v154
	ds_bpermute_b32 v155, v248, v155
	s_waitcnt lgkmcnt(0)
	global_store_dwordx4 v[146:147], v[152:155], off offset:256
	s_and_b64 vcc, exec, s[42:43]
	s_cbranch_vccnz .LBB0_336
	v_mul_f32_e32 v147, 0xbfb8aa3b, v70
	v_mul_f32_e32 v149, 0xbfb8aa3b, v72
	v_mul_f32_e32 v146, 0xbfb8aa3b, v78
	v_exp_f32_e32 v154, v147
	v_mul_f32_e32 v147, 0xbfb8aa3b, v79
	v_mul_f32_e32 v150, 0xbfb8aa3b, v71
	v_mul_f32_e32 v148, 0xbfb8aa3b, v80
	v_exp_f32_e32 v162, v149
	v_mul_f32_e32 v149, 0xbfb8aa3b, v81
	v_mul_f32_e32 v151, 0xbfb8aa3b, v73
	v_exp_f32_e32 v146, v146
	v_exp_f32_e32 v147, v147
	v_exp_f32_e32 v148, v148
	v_exp_f32_e32 v149, v149
	v_exp_f32_e32 v163, v151
	v_exp_f32_e32 v155, v150
	v_pk_add_f32 v[152:153], v[146:147], 1.0 op_sel_hi:[1,0]
	v_pk_add_f32 v[150:151], v[148:149], 1.0 op_sel_hi:[1,0]
	v_pk_add_f32 v[148:149], v[162:163], 1.0 op_sel_hi:[1,0]
	v_pk_add_f32 v[154:155], v[154:155], 1.0 op_sel_hi:[1,0]
	v_add_u32_e32 v146, 48, v161
	v_mad_i64_i32 v[146:147], s[46:47], s14, v146, 0
	v_lshl_add_u64 v[146:147], v[146:147], 1, v[130:131]
	v_cvt_pk_bf16_f32 v152, v152, v153
	v_cvt_pk_bf16_f32 v153, v150, v151
	v_cvt_pk_bf16_f32 v154, v154, v155
	v_cvt_pk_bf16_f32 v155, v148, v149
	s_branch .Lwin_join_5
.LBB0_336:
	v_add_u32_e32 v146, 48, v161
	v_mad_i64_i32 v[146:147], s[46:47], s14, v146, 0
	v_lshl_add_u64 v[146:147], v[146:147], 1, v[130:131]
	v_cvt_pk_bf16_f32 v152, v78, v79
	v_cvt_pk_bf16_f32 v153, v80, v81
	v_cvt_pk_bf16_f32 v154, v70, v71
	v_cvt_pk_bf16_f32 v155, v72, v73
.Lwin_join_5:
	ds_bpermute_b32 v152, v248, v152
	ds_bpermute_b32 v153, v248, v153
	ds_bpermute_b32 v154, v248, v154
	ds_bpermute_b32 v155, v248, v155
	s_waitcnt lgkmcnt(0)
	global_store_dwordx4 v[146:147], v[152:155], off
	s_and_b64 vcc, exec, s[42:43]
	s_cbranch_vccnz .LBB0_338
	v_mul_f32_e32 v149, 0xbfb8aa3b, v66
	v_mul_f32_e32 v151, 0xbfb8aa3b, v68
	v_mul_f32_e32 v148, 0xbfb8aa3b, v74
	v_exp_f32_e32 v154, v149
	v_mul_f32_e32 v149, 0xbfb8aa3b, v75
	v_mul_f32_e32 v152, 0xbfb8aa3b, v67
	v_mul_f32_e32 v150, 0xbfb8aa3b, v76
	v_exp_f32_e32 v162, v151
	v_mul_f32_e32 v151, 0xbfb8aa3b, v77
	v_mul_f32_e32 v153, 0xbfb8aa3b, v69
	v_exp_f32_e32 v148, v148
	v_exp_f32_e32 v149, v149
	v_exp_f32_e32 v150, v150
	v_exp_f32_e32 v151, v151
	v_exp_f32_e32 v163, v153
	v_exp_f32_e32 v155, v152
	v_pk_add_f32 v[152:153], v[148:149], 1.0 op_sel_hi:[1,0]
	v_pk_add_f32 v[150:151], v[150:151], 1.0 op_sel_hi:[1,0]
	v_pk_add_f32 v[148:149], v[162:163], 1.0 op_sel_hi:[1,0]
	v_pk_add_f32 v[154:155], v[154:155], 1.0 op_sel_hi:[1,0]
	v_cvt_pk_bf16_f32 v152, v152, v153
	v_cvt_pk_bf16_f32 v153, v150, v151
	s_nop 0
	v_cvt_pk_bf16_f32 v154, v154, v155
	v_cvt_pk_bf16_f32 v155, v148, v149
	s_branch .Lwin_join_6
; __device__ __forceinline__ unsigned cvt_pk_bf16(float lo, float hi) { unsigned r; asm volatile("v_cvt_pk_bf16_f32 %0, %1, %2" : "=v"(r) : "v"(lo), "v"(hi)); return r; }
;     __device__ __forceinline__ void operator()(const f32x4 (&acc)[2][2][4][2], const Unit& u, int wr, int wc, int fr, int fq) const {
;         const int row0 = u.pm * BM + wr * 64 + fr; const bool isg = u.pn >= 30;
;         bf16_t* base = isg ? Gt : Z; const int ld = isg ? 3072 : 7680; const int col0 = (isg ? (u.pn - 30) : u.pn) * BM + wc * 32 + 8 * fq;
; #pragma unroll
;         for (int ai = 0; ai < 2; ++ai)
; #pragma unroll
;             for (int m = 0; m < 4; ++m)
; #pragma unroll
;                 for (int bj = 0; bj < 2; ++bj) {
;                     f32x4 v0 = acc[ai][bj][m][0], v1 = acc[ai][bj][m][1];
;                     if (isg) {
; #pragma unroll
;                         for (int j = 0; j < 4; ++j) { v0[j] = 1.f + __builtin_amdgcn_exp2f(v0[j] * -1.44269504088896341f); v1[j] = 1.f + __builtin_amdgcn_exp2f(v1[j] * -1.44269504088896341f); }
;                     }
;                     u32x4 w; w.x = cvt_pk_bf16(v0[0], v0[1]); w.y = cvt_pk_bf16(v0[2], v0[3]); w.z = cvt_pk_bf16(v1[0], v1[1]); w.w = cvt_pk_bf16(v1[2], v1[3]);
;                     *(u32x4*)(base + (size_t)(row0 + ai * HALF + m * 16) * ld + col0 + bj * HALF) = w;
;                 }
;     }
.LBB0_338:
	v_cvt_pk_bf16_f32 v152, v74, v75
	v_cvt_pk_bf16_f32 v153, v76, v77
	s_nop 0
	v_cvt_pk_bf16_f32 v154, v66, v67
	v_cvt_pk_bf16_f32 v155, v68, v69
.Lwin_join_6:
	ds_bpermute_b32 v152, v248, v152
	ds_bpermute_b32 v153, v248, v153
	ds_bpermute_b32 v154, v248, v154
	ds_bpermute_b32 v155, v248, v155
	s_waitcnt lgkmcnt(0)
	global_store_dwordx4 v[146:147], v[152:155], off offset:256
	s_and_b64 vcc, exec, s[42:43]
	s_cbranch_vccnz .LBB0_340
	v_mul_f32_e32 v147, 0xbfb8aa3b, v54
	v_mul_f32_e32 v149, 0xbfb8aa3b, v56
	v_mul_f32_e32 v146, 0xbfb8aa3b, v62
	v_exp_f32_e32 v154, v147
	v_mul_f32_e32 v147, 0xbfb8aa3b, v63
	v_mul_f32_e32 v150, 0xbfb8aa3b, v55
	v_mul_f32_e32 v148, 0xbfb8aa3b, v64
	v_exp_f32_e32 v162, v149
	v_mul_f32_e32 v149, 0xbfb8aa3b, v65
	v_mul_f32_e32 v151, 0xbfb8aa3b, v57
	v_exp_f32_e32 v146, v146
	v_exp_f32_e32 v147, v147
	v_exp_f32_e32 v148, v148
	v_exp_f32_e32 v149, v149
	v_exp_f32_e32 v163, v151
	v_exp_f32_e32 v155, v150
	v_pk_add_f32 v[152:153], v[146:147], 1.0 op_sel_hi:[1,0]
	v_pk_add_f32 v[150:151], v[148:149], 1.0 op_sel_hi:[1,0]
	v_pk_add_f32 v[148:149], v[162:163], 1.0 op_sel_hi:[1,0]
	v_pk_add_f32 v[154:155], v[154:155], 1.0 op_sel_hi:[1,0]
	v_add_u32_e32 v146, 0x80, v161
	v_mad_i64_i32 v[146:147], s[46:47], s14, v146, 0
	v_lshl_add_u64 v[146:147], v[146:147], 1, v[130:131]
	v_cvt_pk_bf16_f32 v152, v152, v153
	v_cvt_pk_bf16_f32 v153, v150, v151
	v_cvt_pk_bf16_f32 v154, v154, v155
	v_cvt_pk_bf16_f32 v155, v148, v149
	s_branch .Lwin_join_7
.LBB0_340:
	v_add_u32_e32 v146, 0x80, v161
	v_mad_i64_i32 v[146:147], s[46:47], s14, v146, 0
	v_lshl_add_u64 v[146:147], v[146:147], 1, v[130:131]
	v_cvt_pk_bf16_f32 v152, v62, v63
	v_cvt_pk_bf16_f32 v153, v64, v65
	v_cvt_pk_bf16_f32 v154, v54, v55
	v_cvt_pk_bf16_f32 v155, v56, v57
.Lwin_join_7:
	ds_bpermute_b32 v152, v248, v152
	ds_bpermute_b32 v153, v248, v153
	ds_bpermute_b32 v154, v248, v154
	ds_bpermute_b32 v155, v248, v155
	s_waitcnt lgkmcnt(0)
	global_store_dwordx4 v[146:147], v[152:155], off
	s_and_b64 vcc, exec, s[42:43]
	s_cbranch_vccnz .LBB0_342
	v_mul_f32_e32 v149, 0xbfb8aa3b, v50
	v_mul_f32_e32 v151, 0xbfb8aa3b, v52
	v_mul_f32_e32 v148, 0xbfb8aa3b, v58
	v_exp_f32_e32 v154, v149
	v_mul_f32_e32 v149, 0xbfb8aa3b, v59
	v_mul_f32_e32 v152, 0xbfb8aa3b, v51
	v_mul_f32_e32 v150, 0xbfb8aa3b, v60
	v_exp_f32_e32 v162, v151
	v_mul_f32_e32 v151, 0xbfb8aa3b, v61
	v_mul_f32_e32 v153, 0xbfb8aa3b, v53
	v_exp_f32_e32 v148, v148
	v_exp_f32_e32 v149, v149
	v_exp_f32_e32 v150, v150
	v_exp_f32_e32 v151, v151
	v_exp_f32_e32 v163, v153
	v_exp_f32_e32 v155, v152
	v_pk_add_f32 v[152:153], v[148:149], 1.0 op_sel_hi:[1,0]
	v_pk_add_f32 v[150:151], v[150:151], 1.0 op_sel_hi:[1,0]
	v_pk_add_f32 v[148:149], v[162:163], 1.0 op_sel_hi:[1,0]
	v_pk_add_f32 v[154:155], v[154:155], 1.0 op_sel_hi:[1,0]
	v_cvt_pk_bf16_f32 v152, v152, v153
	v_cvt_pk_bf16_f32 v153, v150, v151
	s_nop 0
	v_cvt_pk_bf16_f32 v154, v154, v155
	v_cvt_pk_bf16_f32 v155, v148, v149
	s_branch .Lwin_join_8
.LBB0_342:
	v_cvt_pk_bf16_f32 v152, v58, v59
	v_cvt_pk_bf16_f32 v153, v60, v61
	s_nop 0
	v_cvt_pk_bf16_f32 v154, v50, v51
	v_cvt_pk_bf16_f32 v155, v52, v53
.Lwin_join_8:
	ds_bpermute_b32 v152, v248, v152
	ds_bpermute_b32 v153, v248, v153
	ds_bpermute_b32 v154, v248, v154
	ds_bpermute_b32 v155, v248, v155
	s_waitcnt lgkmcnt(0)
	global_store_dwordx4 v[146:147], v[152:155], off offset:256
	s_and_b64 vcc, exec, s[42:43]
	s_cbranch_vccnz .LBB0_344
	v_mul_f32_e32 v147, 0xbfb8aa3b, v38
	v_mul_f32_e32 v149, 0xbfb8aa3b, v40
	v_mul_f32_e32 v146, 0xbfb8aa3b, v46
	v_exp_f32_e32 v154, v147
	v_mul_f32_e32 v147, 0xbfb8aa3b, v47
	v_mul_f32_e32 v150, 0xbfb8aa3b, v39
	v_mul_f32_e32 v148, 0xbfb8aa3b, v48
	v_exp_f32_e32 v162, v149
	v_mul_f32_e32 v149, 0xbfb8aa3b, v49
	v_mul_f32_e32 v151, 0xbfb8aa3b, v41
	v_exp_f32_e32 v146, v146
	v_exp_f32_e32 v147, v147
	v_exp_f32_e32 v148, v148
	v_exp_f32_e32 v149, v149
	v_exp_f32_e32 v163, v151
	v_exp_f32_e32 v155, v150
	v_pk_add_f32 v[152:153], v[146:147], 1.0 op_sel_hi:[1,0]
	v_pk_add_f32 v[150:151], v[148:149], 1.0 op_sel_hi:[1,0]
	v_pk_add_f32 v[148:149], v[162:163], 1.0 op_sel_hi:[1,0]
	v_pk_add_f32 v[154:155], v[154:155], 1.0 op_sel_hi:[1,0]
	v_add_u32_e32 v146, 0x90, v161
	v_mad_i64_i32 v[146:147], s[46:47], s14, v146, 0
	v_lshl_add_u64 v[146:147], v[146:147], 1, v[130:131]
	v_cvt_pk_bf16_f32 v152, v152, v153
	v_cvt_pk_bf16_f32 v153, v150, v151
	v_cvt_pk_bf16_f32 v154, v154, v155
	v_cvt_pk_bf16_f32 v155, v148, v149
	s_branch .Lwin_join_9
.LBB0_344:
	v_add_u32_e32 v146, 0x90, v161
	v_mad_i64_i32 v[146:147], s[46:47], s14, v146, 0
	v_lshl_add_u64 v[146:147], v[146:147], 1, v[130:131]
	v_cvt_pk_bf16_f32 v152, v46, v47
	v_cvt_pk_bf16_f32 v153, v48, v49
	v_cvt_pk_bf16_f32 v154, v38, v39
	v_cvt_pk_bf16_f32 v155, v40, v41
.Lwin_join_9:
	ds_bpermute_b32 v152, v248, v152
	ds_bpermute_b32 v153, v248, v153
	ds_bpermute_b32 v154, v248, v154
	ds_bpermute_b32 v155, v248, v155
	s_waitcnt lgkmcnt(0)
	global_store_dwordx4 v[146:147], v[152:155], off
	s_and_b64 vcc, exec, s[42:43]
	s_cbranch_vccnz .LBB0_346
	v_mul_f32_e32 v149, 0xbfb8aa3b, v34
	v_mul_f32_e32 v151, 0xbfb8aa3b, v36
	v_mul_f32_e32 v148, 0xbfb8aa3b, v42
	v_exp_f32_e32 v154, v149
	v_mul_f32_e32 v149, 0xbfb8aa3b, v43
	v_mul_f32_e32 v152, 0xbfb8aa3b, v35
	v_mul_f32_e32 v150, 0xbfb8aa3b, v44
	v_exp_f32_e32 v162, v151
	v_mul_f32_e32 v151, 0xbfb8aa3b, v45
	v_mul_f32_e32 v153, 0xbfb8aa3b, v37
	v_exp_f32_e32 v148, v148
	v_exp_f32_e32 v149, v149
	v_exp_f32_e32 v150, v150
	v_exp_f32_e32 v151, v151
	v_exp_f32_e32 v163, v153
	v_exp_f32_e32 v155, v152
	v_pk_add_f32 v[152:153], v[148:149], 1.0 op_sel_hi:[1,0]
	v_pk_add_f32 v[150:151], v[150:151], 1.0 op_sel_hi:[1,0]
	v_pk_add_f32 v[148:149], v[162:163], 1.0 op_sel_hi:[1,0]
	v_pk_add_f32 v[154:155], v[154:155], 1.0 op_sel_hi:[1,0]
	v_cvt_pk_bf16_f32 v152, v152, v153
	v_cvt_pk_bf16_f32 v153, v150, v151
	s_nop 0
	v_cvt_pk_bf16_f32 v154, v154, v155
	v_cvt_pk_bf16_f32 v155, v148, v149
	s_branch .Lwin_join_10
; __device__ __forceinline__ unsigned cvt_pk_bf16(float lo, float hi) { unsigned r; asm volatile("v_cvt_pk_bf16_f32 %0, %1, %2" : "=v"(r) : "v"(lo), "v"(hi)); return r; }
;     __device__ __forceinline__ void operator()(const f32x4 (&acc)[2][2][4][2], const Unit& u, int wr, int wc, int fr, int fq) const {
;         const int row0 = u.pm * BM + wr * 64 + fr; const bool isg = u.pn >= 30;
;         bf16_t* base = isg ? Gt : Z; const int ld = isg ? 3072 : 7680; const int col0 = (isg ? (u.pn - 30) : u.pn) * BM + wc * 32 + 8 * fq;
; #pragma unroll
;         for (int ai = 0; ai < 2; ++ai)
; #pragma unroll
;             for (int m = 0; m < 4; ++m)
; #pragma unroll
;                 for (int bj = 0; bj < 2; ++bj) {
;                     f32x4 v0 = acc[ai][bj][m][0], v1 = acc[ai][bj][m][1];
;                     if (isg) {
; #pragma unroll
;                         for (int j = 0; j < 4; ++j) { v0[j] = 1.f + __builtin_amdgcn_exp2f(v0[j] * -1.44269504088896341f); v1[j] = 1.f + __builtin_amdgcn_exp2f(v1[j] * -1.44269504088896341f); }
;                     }
;                     u32x4 w; w.x = cvt_pk_bf16(v0[0], v0[1]); w.y = cvt_pk_bf16(v0[2], v0[3]); w.z = cvt_pk_bf16(v1[0], v1[1]); w.w = cvt_pk_bf16(v1[2], v1[3]);
;                     *(u32x4*)(base + (size_t)(row0 + ai * HALF + m * 16) * ld + col0 + bj * HALF) = w;
;                 }
;     }
.LBB0_346:
	v_cvt_pk_bf16_f32 v152, v42, v43
	v_cvt_pk_bf16_f32 v153, v44, v45
	s_nop 0
	v_cvt_pk_bf16_f32 v154, v34, v35
	v_cvt_pk_bf16_f32 v155, v36, v37
.Lwin_join_10:
	ds_bpermute_b32 v152, v248, v152
	ds_bpermute_b32 v153, v248, v153
	ds_bpermute_b32 v154, v248, v154
	ds_bpermute_b32 v155, v248, v155
	s_waitcnt lgkmcnt(0)
	global_store_dwordx4 v[146:147], v[152:155], off offset:256
	s_and_b64 vcc, exec, s[42:43]
	s_cbranch_vccnz .LBB0_348
	v_mul_f32_e32 v147, 0xbfb8aa3b, v22
	v_mul_f32_e32 v149, 0xbfb8aa3b, v24
	v_mul_f32_e32 v146, 0xbfb8aa3b, v30
	v_exp_f32_e32 v154, v147
	v_mul_f32_e32 v147, 0xbfb8aa3b, v31
	v_mul_f32_e32 v150, 0xbfb8aa3b, v23
	v_mul_f32_e32 v148, 0xbfb8aa3b, v32
	v_exp_f32_e32 v162, v149
	v_mul_f32_e32 v149, 0xbfb8aa3b, v33
	v_mul_f32_e32 v151, 0xbfb8aa3b, v25
	v_exp_f32_e32 v146, v146
	v_exp_f32_e32 v147, v147
	v_exp_f32_e32 v148, v148
	v_exp_f32_e32 v149, v149
	v_exp_f32_e32 v163, v151
	v_exp_f32_e32 v155, v150
	v_pk_add_f32 v[152:153], v[146:147], 1.0 op_sel_hi:[1,0]
	v_pk_add_f32 v[150:151], v[148:149], 1.0 op_sel_hi:[1,0]
	v_pk_add_f32 v[148:149], v[162:163], 1.0 op_sel_hi:[1,0]
	v_pk_add_f32 v[154:155], v[154:155], 1.0 op_sel_hi:[1,0]
	v_add_u32_e32 v146, 0xa0, v161
	v_mad_i64_i32 v[146:147], s[46:47], s14, v146, 0
	v_lshl_add_u64 v[146:147], v[146:147], 1, v[130:131]
	v_cvt_pk_bf16_f32 v152, v152, v153
	v_cvt_pk_bf16_f32 v153, v150, v151
	v_cvt_pk_bf16_f32 v154, v154, v155
	v_cvt_pk_bf16_f32 v155, v148, v149
	s_branch .Lwin_join_11
.LBB0_348:
	v_add_u32_e32 v146, 0xa0, v161
	v_mad_i64_i32 v[146:147], s[46:47], s14, v146, 0
	v_lshl_add_u64 v[146:147], v[146:147], 1, v[130:131]
	v_cvt_pk_bf16_f32 v152, v30, v31
	v_cvt_pk_bf16_f32 v153, v32, v33
	v_cvt_pk_bf16_f32 v154, v22, v23
	v_cvt_pk_bf16_f32 v155, v24, v25
.Lwin_join_11:
	ds_bpermute_b32 v152, v248, v152
	ds_bpermute_b32 v153, v248, v153
	ds_bpermute_b32 v154, v248, v154
	ds_bpermute_b32 v155, v248, v155
	s_waitcnt lgkmcnt(0)
	global_store_dwordx4 v[146:147], v[152:155], off
	s_and_b64 vcc, exec, s[42:43]
	s_cbranch_vccnz .LBB0_350
	v_mul_f32_e32 v149, 0xbfb8aa3b, v18
	v_mul_f32_e32 v151, 0xbfb8aa3b, v20
	v_mul_f32_e32 v148, 0xbfb8aa3b, v26
	v_exp_f32_e32 v154, v149
	v_mul_f32_e32 v149, 0xbfb8aa3b, v27
	v_mul_f32_e32 v152, 0xbfb8aa3b, v19
	v_mul_f32_e32 v150, 0xbfb8aa3b, v28
	v_exp_f32_e32 v162, v151
	v_mul_f32_e32 v151, 0xbfb8aa3b, v29
	v_mul_f32_e32 v153, 0xbfb8aa3b, v21
	v_exp_f32_e32 v148, v148
	v_exp_f32_e32 v149, v149
	v_exp_f32_e32 v150, v150
	v_exp_f32_e32 v151, v151
	v_exp_f32_e32 v163, v153
	v_exp_f32_e32 v155, v152
	v_pk_add_f32 v[152:153], v[148:149], 1.0 op_sel_hi:[1,0]
	v_pk_add_f32 v[150:151], v[150:151], 1.0 op_sel_hi:[1,0]
	v_pk_add_f32 v[148:149], v[162:163], 1.0 op_sel_hi:[1,0]
	v_pk_add_f32 v[154:155], v[154:155], 1.0 op_sel_hi:[1,0]
	v_cvt_pk_bf16_f32 v152, v152, v153
	v_cvt_pk_bf16_f32 v153, v150, v151
	s_nop 0
	v_cvt_pk_bf16_f32 v154, v154, v155
	v_cvt_pk_bf16_f32 v155, v148, v149
	s_branch .Lwin_join_12
.LBB0_350:
	v_cvt_pk_bf16_f32 v152, v26, v27
	v_cvt_pk_bf16_f32 v153, v28, v29
	s_nop 0
	v_cvt_pk_bf16_f32 v154, v18, v19
	v_cvt_pk_bf16_f32 v155, v20, v21
.Lwin_join_12:
	ds_bpermute_b32 v152, v248, v152
	ds_bpermute_b32 v153, v248, v153
	ds_bpermute_b32 v154, v248, v154
	ds_bpermute_b32 v155, v248, v155
	s_waitcnt lgkmcnt(0)
	global_store_dwordx4 v[146:147], v[152:155], off offset:256
	s_and_b64 vcc, exec, s[42:43]
	s_cbranch_vccnz .LBB0_352
	v_mul_f32_e32 v147, 0xbfb8aa3b, v6
	v_mul_f32_e32 v149, 0xbfb8aa3b, v8
	v_mul_f32_e32 v146, 0xbfb8aa3b, v14
	v_exp_f32_e32 v152, v147
	v_mul_f32_e32 v147, 0xbfb8aa3b, v15
	v_mul_f32_e32 v150, 0xbfb8aa3b, v7
	v_mul_f32_e32 v148, 0xbfb8aa3b, v16
	v_exp_f32_e32 v154, v149
	v_mul_f32_e32 v149, 0xbfb8aa3b, v17
	v_mul_f32_e32 v151, 0xbfb8aa3b, v9
	v_exp_f32_e32 v146, v146
	v_exp_f32_e32 v147, v147
	v_exp_f32_e32 v148, v148
	v_exp_f32_e32 v149, v149
	v_exp_f32_e32 v155, v151
	v_exp_f32_e32 v153, v150
	v_pk_add_f32 v[150:151], v[146:147], 1.0 op_sel_hi:[1,0]
	v_pk_add_f32 v[148:149], v[148:149], 1.0 op_sel_hi:[1,0]
	v_pk_add_f32 v[146:147], v[154:155], 1.0 op_sel_hi:[1,0]
	v_pk_add_f32 v[152:153], v[152:153], 1.0 op_sel_hi:[1,0]
	v_add_u32_e32 v154, 0xb0, v161
	v_mad_i64_i32 v[154:155], s[14:15], s14, v154, 0
	v_lshl_add_u64 v[130:131], v[154:155], 1, v[130:131]
	v_cvt_pk_bf16_f32 v150, v150, v151
	v_cvt_pk_bf16_f32 v151, v148, v149
	v_cvt_pk_bf16_f32 v152, v152, v153
	v_cvt_pk_bf16_f32 v153, v146, v147
	s_branch .Lwin_join_13
.LBB0_352:
	v_add_u32_e32 v154, 0xb0, v161
	v_mad_i64_i32 v[154:155], s[14:15], s14, v154, 0
	v_lshl_add_u64 v[130:131], v[154:155], 1, v[130:131]
	v_cvt_pk_bf16_f32 v150, v14, v15
	v_cvt_pk_bf16_f32 v151, v16, v17
	v_cvt_pk_bf16_f32 v152, v6, v7
	v_cvt_pk_bf16_f32 v153, v8, v9
.Lwin_join_13:
	ds_bpermute_b32 v150, v248, v150
	ds_bpermute_b32 v151, v248, v151
	ds_bpermute_b32 v152, v248, v152
	ds_bpermute_b32 v153, v248, v153
	s_waitcnt lgkmcnt(0)
	global_store_dwordx4 v[130:131], v[150:153], off
	s_and_b64 vcc, exec, s[42:43]
	s_cbranch_vccnz .LBB0_354
	v_mul_f32_e32 v147, 0xbfb8aa3b, v2
	v_mul_f32_e32 v149, 0xbfb8aa3b, v4
	v_mul_f32_e32 v146, 0xbfb8aa3b, v10
	v_exp_f32_e32 v150, v147
	v_mul_f32_e32 v147, 0xbfb8aa3b, v11
	v_mul_f32_e32 v151, 0xbfb8aa3b, v3
	v_mul_f32_e32 v148, 0xbfb8aa3b, v12
	v_exp_f32_e32 v154, v149
	v_mul_f32_e32 v149, 0xbfb8aa3b, v13
	v_mul_f32_e32 v152, 0xbfb8aa3b, v5
	v_exp_f32_e32 v146, v146
	v_exp_f32_e32 v147, v147
	v_exp_f32_e32 v148, v148
	v_exp_f32_e32 v149, v149
	v_exp_f32_e32 v155, v152
	v_exp_f32_e32 v151, v151
	v_pk_add_f32 v[152:153], v[146:147], 1.0 op_sel_hi:[1,0]
	v_pk_add_f32 v[148:149], v[148:149], 1.0 op_sel_hi:[1,0]
	v_pk_add_f32 v[146:147], v[154:155], 1.0 op_sel_hi:[1,0]
	v_pk_add_f32 v[150:151], v[150:151], 1.0 op_sel_hi:[1,0]
	v_cvt_pk_bf16_f32 v152, v152, v153
	v_cvt_pk_bf16_f32 v153, v148, v149
	s_nop 0
	v_cvt_pk_bf16_f32 v154, v150, v151
	v_cvt_pk_bf16_f32 v155, v146, v147
	s_branch .Lwin_join_14
.LBB0_354:
	v_cvt_pk_bf16_f32 v152, v10, v11
	v_cvt_pk_bf16_f32 v153, v12, v13
	s_nop 0
	v_cvt_pk_bf16_f32 v154, v2, v3
	v_cvt_pk_bf16_f32 v155, v4, v5
.Lwin_join_14:
	ds_bpermute_b32 v152, v248, v152
	ds_bpermute_b32 v153, v248, v153
	ds_bpermute_b32 v154, v248, v154
	ds_bpermute_b32 v155, v248, v155
	s_waitcnt lgkmcnt(0)
	global_store_dwordx4 v[130:131], v[152:155], off offset:256
	s_branch .LBB0_356
